# speedup vs baseline: 1.0188x; 1.0077x over previous
; __device__ __forceinline__ void transpose_tile(const float* __restrict__ W, bf16* __restrict__ Wt, int K, int N,
;                                                int k0, int n0, float* tile, int wv) {
;     ...
;   const int r = tid >> 6, c4 = tid & 63;
;   const int n = n0 + c4 * 4;
;   float4 v[8];
; #pragma unroll
;   for (int i = 0; i < 8; ++i) {
;     if (n < N) v[i] = *(const float4*)(W + (long)(k0 + r + 8 * i) * N + n);
;     else v[i] = make_float4(0.f, 0.f, 0.f, 0.f);
;   }
; __device__ __forceinline__ void transpose_phase(KP p, float* lds, int bid, int nb, int wv) {
;     ...
;     if (j < t1) {
;       int kt = j / 57, nt = j % 57;
;       transpose_tile(p->w_in, p->Wt1, D, PW, kt * 64, nt * 256, lds, wv);
.LBB0_23:
	s_mul_hi_i32 s6, s19, 0x8fb823ef
	s_add_i32 s6, s6, s19
	s_lshr_b32 s7, s6, 31
	s_ashr_i32 s6, s6, 5
	s_add_i32 s20, s6, s7
	v_mbcnt_lo_u32_b32 v34, -1, 0
	v_mbcnt_hi_u32_b32 v34, -1, v34
	s_lshl_b32 s6, s20, 6
	v_lshlrev_b32_e32 v2, 2, v34
	v_and_b32_e32 v40, 0xfc, v2
	s_mulk_i32 s20, 0x3900
	v_readlane_b32 s7, v253, 3
	v_subrev_u32_e32 v2, s20, v40
	v_add_u32_e32 v2, s12, v2
	v_or_b32_e32 v38, s7, v34
	v_ashrrev_i32_e32 v39, 6, v38
	v_ashrrev_i32_e32 v3, 31, v2
	v_cmp_gt_i32_e32 vcc, s14, v2
	v_add_u32_e32 v41, s6, v39
	v_lshl_add_u64 v[36:37], v[2:3], 2, s[2:3]
	v_mov_b32_e32 v2, 0
	v_mov_b32_e32 v3, 0
	v_mov_b32_e32 v4, 0
	v_mov_b32_e32 v5, 0
	s_and_saveexec_b64 s[10:11], vcc
	s_cbranch_execz .LBB0_25
	v_mad_i64_i32 v[2:3], s[22:23], v41, s15, v[36:37]
	global_load_dwordx4 v[2:5], v[2:3], off nt
.LBB0_25:
	s_or_b64 exec, exec, s[10:11]
	v_mov_b32_e32 v6, 0
	v_mov_b32_e32 v10, 0
	v_mov_b32_e32 v11, 0
	v_mov_b32_e32 v12, 0
	v_mov_b32_e32 v13, 0
	s_and_saveexec_b64 s[10:11], vcc
	s_cbranch_execz .LBB0_27
	v_add_u32_e32 v7, 8, v41
	v_mad_i64_i32 v[8:9], s[22:23], v7, s15, v[36:37]
	global_load_dwordx4 v[10:13], v[8:9], off nt
.LBB0_27:
	s_or_b64 exec, exec, s[10:11]
	v_mov_b32_e32 v7, 0
	v_mov_b32_e32 v8, 0
	v_mov_b32_e32 v9, 0
	s_and_saveexec_b64 s[10:11], vcc
	s_cbranch_execz .LBB0_29
	v_add_u32_e32 v6, 16, v41
	v_mad_i64_i32 v[6:7], s[22:23], v6, s15, v[36:37]
	global_load_dwordx4 v[6:9], v[6:7], off nt
.LBB0_29:
	s_or_b64 exec, exec, s[10:11]
	v_mov_b32_e32 v14, 0
	v_mov_b32_e32 v18, 0
	v_mov_b32_e32 v19, 0
	v_mov_b32_e32 v20, 0
	v_mov_b32_e32 v21, 0
	s_and_saveexec_b64 s[10:11], vcc
	s_cbranch_execz .LBB0_31
	v_add_u32_e32 v15, 24, v41
	v_mad_i64_i32 v[16:17], s[22:23], v15, s15, v[36:37]
	global_load_dwordx4 v[18:21], v[16:17], off nt
.LBB0_31:
	s_or_b64 exec, exec, s[10:11]
	v_mov_b32_e32 v15, 0
	v_mov_b32_e32 v16, 0
	v_mov_b32_e32 v17, 0
	s_and_saveexec_b64 s[10:11], vcc
	s_cbranch_execz .LBB0_33
	v_add_u32_e32 v14, 32, v41
	v_mad_i64_i32 v[14:15], s[22:23], v14, s15, v[36:37]
	global_load_dwordx4 v[14:17], v[14:15], off nt
.LBB0_33:
	s_or_b64 exec, exec, s[10:11]
	v_mov_b32_e32 v22, 0
	v_mov_b32_e32 v26, 0
	v_mov_b32_e32 v27, 0
	v_mov_b32_e32 v28, 0
	v_mov_b32_e32 v29, 0
	s_and_saveexec_b64 s[10:11], vcc
	s_cbranch_execz .LBB0_35
	v_add_u32_e32 v23, 40, v41
	v_mad_i64_i32 v[24:25], s[22:23], v23, s15, v[36:37]
	global_load_dwordx4 v[26:29], v[24:25], off nt
.LBB0_35:
	s_or_b64 exec, exec, s[10:11]
	v_mov_b32_e32 v23, 0
	v_mov_b32_e32 v24, 0
	v_mov_b32_e32 v25, 0
	s_and_saveexec_b64 s[10:11], vcc
	s_cbranch_execz .LBB0_37
	v_add_u32_e32 v22, 48, v41
	v_mad_i64_i32 v[22:23], s[22:23], v22, s15, v[36:37]
	global_load_dwordx4 v[22:25], v[22:23], off nt
.LBB0_37:
	s_or_b64 exec, exec, s[10:11]
	v_mov_b32_e32 v30, 0
	v_mov_b32_e32 v31, 0
	v_mov_b32_e32 v32, 0
	v_mov_b32_e32 v33, 0
	s_and_saveexec_b64 s[10:11], vcc
	s_cbranch_execz .LBB0_39
	v_add_u32_e32 v30, 56, v41
	v_mad_i64_i32 v[30:31], s[22:23], v30, s15, v[36:37]
	global_load_dwordx4 v[30:33], v[30:31], off nt

; template <bool OUTBF>
; __device__ __forceinline__ void rmsnorm_phase(const float* __restrict__ in, const float* __restrict__ w, void* outp, int bid, int nb, int wv) {
;     ...
;   for (int row = bid * 8 + wid; row < T; row += nb * 8) {
;     const float4* pr = (const float4*)(in + (long)row * D);
;     float4 v[16];
;     float ss = 0.f;
; #pragma unroll
;     for (int i = 0; i < 16; ++i) {
;       v[i] = pr[lane + 64 * i];
;       ss += v[i].x * v[i].x + v[i].y * v[i].y + v[i].z * v[i].z + v[i].w * v[i].w;
;     }
;     ss = wavesum(ss, lane);
.LBB0_49:
	global_load_dwordx4 v[66:69], v[86:87], off offset:1024 nt
	global_load_dwordx4 v[70:73], v[86:87], off nt
	global_load_dwordx4 v[78:81], v[86:87], off offset:2048 nt
	global_load_dwordx4 v[74:77], v[86:87], off offset:3072 nt
	v_add_co_u32_e32 v88, vcc, s14, v86
	v_add_u32_e32 v82, s6, v82
	s_nop 0
	v_addc_co_u32_e32 v89, vcc, 0, v87, vcc
	v_add_co_u32_e32 v90, vcc, s13, v86
	s_waitcnt vmcnt(3)
	v_pk_mul_f32 v[144:145], v[68:69], v[68:69]
	v_addc_co_u32_e32 v91, vcc, 0, v87, vcc
	v_add_co_u32_e32 v92, vcc, s12, v86
	s_waitcnt vmcnt(2)
	v_pk_mul_f32 v[146:147], v[70:71], v[70:71]
	v_addc_co_u32_e32 v93, vcc, 0, v87, vcc
	global_load_dwordx4 v[100:103], v[88:89], off nt
	global_load_dwordx4 v[104:107], v[88:89], off offset:1024 nt
	global_load_dwordx4 v[108:111], v[88:89], off offset:2048 nt
	global_load_dwordx4 v[112:115], v[88:89], off offset:3072 nt
	global_load_dwordx4 v[116:119], v[90:91], off offset:1024 nt
	global_load_dwordx4 v[120:123], v[92:93], off offset:-4096 nt
	global_load_dwordx4 v[124:127], v[90:91], off offset:2048 nt
	s_nop 0
	global_load_dwordx4 v[88:91], v[90:91], off offset:3072 nt
	s_nop 0
	global_load_dwordx4 v[128:131], v[92:93], off nt
	global_load_dwordx4 v[132:135], v[92:93], off offset:1024 nt
	global_load_dwordx4 v[136:139], v[92:93], off offset:2048 nt
	global_load_dwordx4 v[140:143], v[92:93], off offset:3072 nt
	v_pk_mul_f32 v[92:93], v[66:67], v[66:67]
	v_pk_mul_f32 v[148:149], v[72:73], v[72:73]
	s_waitcnt vmcnt(13)
	v_pk_mul_f32 v[150:151], v[78:79], v[78:79]
	v_add_f32_e32 v198, v92, v93
	v_add_f32_e32 v199, v146, v147
	v_pk_mul_f32 v[152:153], v[80:81], v[80:81]
	s_waitcnt vmcnt(12)
	v_pk_mul_f32 v[154:155], v[74:75], v[74:75]
	v_add_f32_e32 v200, v150, v151
	v_add_f32_e32 v144, v198, v144
	v_add_f32_e32 v148, v199, v148
	v_pk_mul_f32 v[156:157], v[76:77], v[76:77]
	v_add_f32_e32 v201, v154, v155
	v_add_f32_e32 v152, v200, v152
	v_add_f32_e32 v148, v148, v149
	v_add_f32_e32 v156, v201, v156
	v_add_f32_e32 v149, v152, v153
	v_add_f32_e32 v152, v156, v157
	v_cmp_lt_i32_e32 vcc, s17, v82
	s_or_b64 s[10:11], vcc, s[10:11]
	v_lshl_add_u64 v[86:87], v[86:87], 0, s[4:5]
	s_waitcnt vmcnt(11)
	v_mov_b32_e32 v160, v101
	s_waitcnt vmcnt(10)
	v_mov_b32_e32 v161, v105
	v_mov_b32_e32 v158, v100
	v_mov_b32_e32 v159, v104
	s_waitcnt vmcnt(7)
	v_pk_mul_f32 v[150:151], v[116:117], v[116:117]
	v_pk_mul_f32 v[160:161], v[160:161], v[160:161]
	v_mov_b32_e32 v164, v109
	v_mov_b32_e32 v165, v113
	s_waitcnt vmcnt(6)
	v_pk_mul_f32 v[166:167], v[120:121], v[120:121]
	v_add_f32_e32 v198, v150, v151
	v_pk_fma_f32 v[150:151], v[158:159], v[158:159], v[160:161]
	v_add_f32_e32 v160, v144, v145
	v_mov_b32_e32 v162, v108
	v_mov_b32_e32 v163, v112
	v_pk_mul_f32 v[154:155], v[118:119], v[118:119]
	v_pk_mul_f32 v[168:169], v[122:123], v[122:123]
	v_pk_mul_f32 v[164:165], v[164:165], v[164:165]
	v_add_f32_e32 v166, v166, v167
	v_add_f32_e32 v148, v148, v160
	v_mov_b32_e32 v146, v110
	v_mov_b32_e32 v147, v114
	s_waitcnt vmcnt(5)
	v_pk_mul_f32 v[170:171], v[124:125], v[124:125]
	v_pk_fma_f32 v[158:159], v[162:163], v[162:163], v[164:165]
	v_add_f32_e32 v153, v198, v154
	v_add_f32_e32 v154, v166, v168
	v_add_f32_e32 v148, v148, v149
	v_pk_mul_f32 v[172:173], v[126:127], v[126:127]
	s_waitcnt vmcnt(4)
	v_pk_mul_f32 v[174:175], v[88:89], v[88:89]
	v_add_f32_e32 v167, v170, v171
	v_pk_fma_f32 v[144:145], v[146:147], v[146:147], v[158:159]
	v_add_f32_e32 v147, v154, v169
	v_add_f32_e32 v148, v148, v152
	v_mov_b32_e32 v92, v102
	v_mov_b32_e32 v93, v106
	v_pk_mul_f32 v[176:177], v[90:91], v[90:91]
	s_waitcnt vmcnt(3)
	v_pk_mul_f32 v[178:179], v[128:129], v[128:129]
	v_add_f32_e32 v170, v174, v175
	v_add_f32_e32 v156, v167, v172
	v_add_f32_e32 v146, v153, v155
	v_add_f32_e32 v147, v148, v147
	v_pk_mul_f32 v[180:181], v[130:131], v[130:131]
	s_waitcnt vmcnt(2)
	v_pk_mul_f32 v[182:183], v[132:133], v[132:133]
	v_add_f32_e32 v171, v178, v179
	v_add_f32_e32 v157, v170, v176
	v_pk_fma_f32 v[92:93], v[92:93], v[92:93], v[150:151]
	v_add_f32_e32 v150, v156, v173
	v_add_f32_e32 v146, v147, v146
	v_pk_mul_f32 v[184:185], v[134:135], v[134:135]
	s_waitcnt vmcnt(1)
	v_pk_mul_f32 v[186:187], v[136:137], v[136:137]
	v_add_f32_e32 v174, v182, v183
	v_add_f32_e32 v161, v171, v180
	v_add_f32_e32 v151, v157, v177
	v_add_f32_e32 v146, v146, v150
	v_pk_mul_f32 v[188:189], v[138:139], v[138:139]
	s_waitcnt vmcnt(0)
	v_pk_mul_f32 v[190:191], v[140:141], v[140:141]
	v_add_f32_e32 v175, v186, v187
	v_add_f32_e32 v162, v174, v184
	v_add_f32_e32 v153, v161, v181
	v_add_f32_e32 v146, v146, v151
	v_pk_mul_f32 v[192:193], v[142:143], v[142:143]
	v_add_f32_e32 v178, v190, v191
	v_add_f32_e32 v163, v175, v188
	v_add_f32_e32 v154, v162, v185
	v_add_f32_e32 v146, v146, v153
	v_add_f32_e32 v164, v178, v192
	v_add_f32_e32 v155, v163, v189
	v_add_f32_e32 v146, v146, v154
	v_mov_b32_e32 v194, v103
	v_mov_b32_e32 v195, v107
	v_add_f32_e32 v156, v164, v193
	v_add_f32_e32 v146, v146, v155
	v_pk_fma_f32 v[92:93], v[194:195], v[194:195], v[92:93]
	v_add_f32_e32 v146, v146, v156
	v_mov_b32_e32 v196, v111
	v_mov_b32_e32 v197, v115
	v_add_f32_e32 v92, v146, v92
	v_pk_fma_f32 v[144:145], v[196:197], v[196:197], v[144:145]
	v_add_f32_e32 v92, v92, v93
	v_add_f32_e32 v92, v92, v144
	v_add_f32_e32 v92, v92, v145
	ds_bpermute_b32 v93, v94, v92
	s_waitcnt lgkmcnt(0)
	v_add_f32_e32 v92, v92, v93
	ds_bpermute_b32 v93, v95, v92
	s_waitcnt lgkmcnt(0)
	v_add_f32_e32 v92, v92, v93
	ds_bpermute_b32 v93, v96, v92
	s_waitcnt lgkmcnt(0)
	v_add_f32_e32 v92, v92, v93
	ds_bpermute_b32 v93, v97, v92
	s_waitcnt lgkmcnt(0)
	v_add_f32_e32 v92, v92, v93
	ds_bpermute_b32 v93, v98, v92
	s_waitcnt lgkmcnt(0)
; template <bool OUTBF>
; __device__ __forceinline__ void rmsnorm_phase(const float* __restrict__ in, const float* __restrict__ w, void* outp, int bid, int nb, int wv) {
;     ...
;     ss = wavesum(ss, lane);
;     const float rs = rsqrtf(ss * (1.f / D) + 1e-6f);
; #pragma unroll
;     for (int i = 0; i < 16; ++i) {
;       float4 w4 = ((const float4*)w)[lane + 64 * i];
;       float4 y = make_float4(v[i].x * rs * w4.x, v[i].y * rs * w4.y, v[i].z * rs * w4.z, v[i].w * rs * w4.w);
;       if (OUTBF) {
;         u16x4 o; o[0] = f2bf(y.x); o[1] = f2bf(y.y); o[2] = f2bf(y.z); o[3] = f2bf(y.w);
	v_add_f32_e32 v92, v92, v93
	ds_bpermute_b32 v93, v99, v92
	s_waitcnt lgkmcnt(0)
	v_add_f32_e32 v92, v92, v93
	v_fmamk_f32 v92, v92, 0x39800000, v83
	v_mul_f32_e32 v93, 0x4b800000, v92
	v_cmp_gt_f32_e32 vcc, s7, v92
	s_nop 1
	v_cndmask_b32_e32 v92, v92, v93, vcc
	v_rsq_f32_e32 v92, v92
	s_nop 0
	v_mul_f32_e32 v93, 0x45800000, v92
	v_cndmask_b32_e32 v92, v92, v93, vcc
	v_pk_mul_f32 v[70:71], v[70:71], v[92:93] op_sel_hi:[1,0]
	v_pk_mul_f32 v[72:73], v[72:73], v[92:93] op_sel_hi:[1,0]
	v_pk_mul_f32 v[66:67], v[66:67], v[92:93] op_sel_hi:[1,0]
	v_pk_mul_f32 v[68:69], v[68:69], v[92:93] op_sel_hi:[1,0]
	v_pk_mul_f32 v[78:79], v[78:79], v[92:93] op_sel_hi:[1,0]
	v_pk_mul_f32 v[80:81], v[80:81], v[92:93] op_sel_hi:[1,0]
	v_pk_mul_f32 v[74:75], v[74:75], v[92:93] op_sel_hi:[1,0]
	v_pk_mul_f32 v[76:77], v[76:77], v[92:93] op_sel_hi:[1,0]
	v_pk_mul_f32 v[120:121], v[120:121], v[92:93] op_sel_hi:[1,0]
	v_pk_mul_f32 v[122:123], v[122:123], v[92:93] op_sel_hi:[1,0]
	v_pk_mul_f32 v[116:117], v[116:117], v[92:93] op_sel_hi:[1,0]
	v_pk_mul_f32 v[118:119], v[118:119], v[92:93] op_sel_hi:[1,0]
	v_pk_mul_f32 v[124:125], v[124:125], v[92:93] op_sel_hi:[1,0]
	v_pk_mul_f32 v[126:127], v[126:127], v[92:93] op_sel_hi:[1,0]
	v_pk_mul_f32 v[88:89], v[88:89], v[92:93] op_sel_hi:[1,0]
	v_pk_mul_f32 v[90:91], v[90:91], v[92:93] op_sel_hi:[1,0]
	v_pk_mul_f32 v[128:129], v[128:129], v[92:93] op_sel_hi:[1,0]
	v_pk_mul_f32 v[130:131], v[130:131], v[92:93] op_sel_hi:[1,0]
	v_pk_mul_f32 v[132:133], v[132:133], v[92:93] op_sel_hi:[1,0]
	v_pk_mul_f32 v[134:135], v[134:135], v[92:93] op_sel_hi:[1,0]
	v_pk_mul_f32 v[136:137], v[136:137], v[92:93] op_sel_hi:[1,0]
	v_pk_mul_f32 v[138:139], v[138:139], v[92:93] op_sel_hi:[1,0]
	v_pk_mul_f32 v[140:141], v[140:141], v[92:93] op_sel_hi:[1,0]
	v_pk_mul_f32 v[142:143], v[142:143], v[92:93] op_sel_hi:[1,0]
	v_pk_mul_f32 v[100:101], v[100:101], v[92:93] op_sel_hi:[1,0]
	v_pk_mul_f32 v[102:103], v[102:103], v[92:93] op_sel_hi:[1,0]
	v_pk_mul_f32 v[104:105], v[104:105], v[92:93] op_sel_hi:[1,0]
	v_pk_mul_f32 v[106:107], v[106:107], v[92:93] op_sel_hi:[1,0]
	v_pk_mul_f32 v[108:109], v[108:109], v[92:93] op_sel_hi:[1,0]
	v_pk_mul_f32 v[110:111], v[110:111], v[92:93] op_sel_hi:[1,0]
	v_pk_mul_f32 v[112:113], v[112:113], v[92:93] op_sel_hi:[1,0]
	v_pk_mul_f32 v[92:93], v[114:115], v[92:93] op_sel_hi:[1,0]
	v_pk_mul_f32 v[70:71], v[2:3], v[70:71]
	v_pk_mul_f32 v[72:73], v[4:5], v[72:73]
	v_pk_mul_f32 v[66:67], v[6:7], v[66:67]
	v_pk_mul_f32 v[68:69], v[8:9], v[68:69]
	v_pk_mul_f32 v[78:79], v[10:11], v[78:79]
	v_pk_mul_f32 v[80:81], v[12:13], v[80:81]
	v_pk_mul_f32 v[74:75], v[14:15], v[74:75]
	v_pk_mul_f32 v[76:77], v[16:17], v[76:77]
	v_pk_mul_f32 v[114:115], v[18:19], v[120:121]
	v_pk_mul_f32 v[120:121], v[20:21], v[122:123]
	v_pk_mul_f32 v[116:117], v[22:23], v[116:117]
	v_pk_mul_f32 v[118:119], v[24:25], v[118:119]
	v_pk_mul_f32 v[122:123], v[26:27], v[124:125]
	v_pk_mul_f32 v[124:125], v[28:29], v[126:127]
	v_pk_mul_f32 v[88:89], v[30:31], v[88:89]
	v_pk_mul_f32 v[90:91], v[32:33], v[90:91]
	v_pk_mul_f32 v[126:127], v[34:35], v[128:129]
	v_pk_mul_f32 v[128:129], v[36:37], v[130:131]
	v_pk_mul_f32 v[130:131], v[38:39], v[132:133]
	v_pk_mul_f32 v[132:133], v[40:41], v[134:135]
	v_pk_mul_f32 v[134:135], v[42:43], v[136:137]
	v_pk_mul_f32 v[136:137], v[44:45], v[138:139]
	v_pk_mul_f32 v[138:139], v[46:47], v[140:141]
	v_pk_mul_f32 v[140:141], v[48:49], v[142:143]
	v_pk_mul_f32 v[100:101], v[50:51], v[100:101]
	v_pk_mul_f32 v[102:103], v[52:53], v[102:103]
	v_pk_mul_f32 v[104:105], v[54:55], v[104:105]
	v_pk_mul_f32 v[106:107], v[56:57], v[106:107]
	v_pk_mul_f32 v[108:109], v[58:59], v[108:109]
	v_pk_mul_f32 v[110:111], v[60:61], v[110:111]
	v_pk_mul_f32 v[112:113], v[62:63], v[112:113]
	v_pk_mul_f32 v[92:93], v[64:65], v[92:93]
	v_bfe_u32 v142, v70, 16, 1
	v_bfe_u32 v143, v71, 16, 1
	v_bfe_u32 v144, v72, 16, 1
	v_bfe_u32 v145, v73, 16, 1
	v_bfe_u32 v146, v66, 16, 1
	v_bfe_u32 v147, v67, 16, 1
	v_bfe_u32 v148, v68, 16, 1
	v_bfe_u32 v149, v69, 16, 1
	v_bfe_u32 v150, v78, 16, 1
	v_bfe_u32 v151, v79, 16, 1
	v_bfe_u32 v152, v80, 16, 1
	v_bfe_u32 v153, v81, 16, 1
	v_bfe_u32 v154, v74, 16, 1
	v_bfe_u32 v155, v75, 16, 1
	v_bfe_u32 v156, v76, 16, 1
	v_bfe_u32 v157, v77, 16, 1
	v_bfe_u32 v158, v114, 16, 1
	v_bfe_u32 v159, v115, 16, 1
	v_bfe_u32 v160, v120, 16, 1
	v_bfe_u32 v161, v121, 16, 1
	v_bfe_u32 v162, v116, 16, 1
	v_bfe_u32 v163, v117, 16, 1
	v_bfe_u32 v164, v118, 16, 1
	v_bfe_u32 v165, v119, 16, 1
	v_bfe_u32 v166, v122, 16, 1
	v_bfe_u32 v167, v123, 16, 1
	v_bfe_u32 v168, v124, 16, 1
	v_bfe_u32 v169, v125, 16, 1
	v_bfe_u32 v170, v88, 16, 1
	v_bfe_u32 v171, v89, 16, 1
	v_bfe_u32 v172, v90, 16, 1
	v_bfe_u32 v173, v91, 16, 1
	v_bfe_u32 v174, v126, 16, 1
	v_bfe_u32 v175, v127, 16, 1
	v_bfe_u32 v176, v128, 16, 1
	v_bfe_u32 v177, v129, 16, 1
	v_bfe_u32 v178, v130, 16, 1
	v_bfe_u32 v179, v131, 16, 1
	v_bfe_u32 v180, v132, 16, 1
	v_bfe_u32 v181, v133, 16, 1
; template <bool OUTBF>
; __device__ __forceinline__ void rmsnorm_phase(const float* __restrict__ in, const float* __restrict__ w, void* outp, int bid, int nb, int wv) {
;     ...
;       float4 y = make_float4(v[i].x * rs * w4.x, v[i].y * rs * w4.y, v[i].z * rs * w4.z, v[i].w * rs * w4.w);
;       if (OUTBF) {
;         u16x4 o; o[0] = f2bf(y.x); o[1] = f2bf(y.y); o[2] = f2bf(y.z); o[3] = f2bf(y.w);
;         *(u16x4*)((bf16*)outp + (long)row * D + (lane + 64 * i) * 4) = o;
;       } else {
;         ((float4*)((float*)outp + (long)row * D))[lane + 64 * i] = y;
;       }
;     }
	v_bfe_u32 v182, v134, 16, 1
	v_bfe_u32 v183, v135, 16, 1
	v_bfe_u32 v184, v136, 16, 1
	v_bfe_u32 v185, v137, 16, 1
	v_bfe_u32 v186, v138, 16, 1
	v_bfe_u32 v187, v139, 16, 1
	v_bfe_u32 v188, v140, 16, 1
	v_bfe_u32 v189, v141, 16, 1
	v_bfe_u32 v190, v100, 16, 1
	v_bfe_u32 v191, v101, 16, 1
	v_bfe_u32 v192, v102, 16, 1
	v_bfe_u32 v193, v103, 16, 1
	v_bfe_u32 v194, v104, 16, 1
	v_bfe_u32 v195, v105, 16, 1
	v_bfe_u32 v196, v106, 16, 1
	v_bfe_u32 v197, v107, 16, 1
	v_bfe_u32 v198, v108, 16, 1
	v_bfe_u32 v199, v109, 16, 1
	v_bfe_u32 v200, v110, 16, 1
	v_bfe_u32 v201, v111, 16, 1
	v_bfe_u32 v202, v112, 16, 1
	v_bfe_u32 v203, v113, 16, 1
	v_bfe_u32 v204, v92, 16, 1
	v_bfe_u32 v205, v93, 16, 1
	v_add3_u32 v70, v70, v142, s15
	v_add3_u32 v71, v71, v143, s15
	v_add3_u32 v72, v72, v144, s15
	v_add3_u32 v73, v73, v145, s15
	v_add3_u32 v142, v66, v146, s15
	v_add3_u32 v143, v67, v147, s15
	v_add3_u32 v68, v68, v148, s15
	v_add3_u32 v69, v69, v149, s15
	v_add3_u32 v78, v78, v150, s15
	v_add3_u32 v79, v79, v151, s15
	v_add3_u32 v80, v80, v152, s15
	v_add3_u32 v81, v81, v153, s15
	v_add3_u32 v74, v74, v154, s15
	v_add3_u32 v75, v75, v155, s15
	v_add3_u32 v76, v76, v156, s15
	v_add3_u32 v77, v77, v157, s15
	v_add3_u32 v114, v114, v158, s15
	v_add3_u32 v115, v115, v159, s15
	v_add3_u32 v120, v120, v160, s15
	v_add3_u32 v121, v121, v161, s15
	v_add3_u32 v116, v116, v162, s15
	v_add3_u32 v117, v117, v163, s15
	v_add3_u32 v118, v118, v164, s15
	v_add3_u32 v119, v119, v165, s15
	v_add3_u32 v122, v122, v166, s15
	v_add3_u32 v123, v123, v167, s15
	v_add3_u32 v124, v124, v168, s15
	v_add3_u32 v125, v125, v169, s15
	v_add3_u32 v88, v88, v170, s15
	v_add3_u32 v89, v89, v171, s15
	v_add3_u32 v90, v90, v172, s15
	v_add3_u32 v91, v91, v173, s15
	v_add3_u32 v126, v126, v174, s15
	v_add3_u32 v127, v127, v175, s15
	v_add3_u32 v128, v128, v176, s15
	v_add3_u32 v129, v129, v177, s15
	v_add3_u32 v130, v130, v178, s15
	v_add3_u32 v131, v131, v179, s15
	v_add3_u32 v132, v132, v180, s15
	v_add3_u32 v133, v133, v181, s15
	v_add3_u32 v134, v134, v182, s15
	v_add3_u32 v135, v135, v183, s15
	v_add3_u32 v136, v136, v184, s15
	v_add3_u32 v137, v137, v185, s15
	v_add3_u32 v138, v138, v186, s15
	v_add3_u32 v139, v139, v187, s15
	v_add3_u32 v140, v140, v188, s15
	v_add3_u32 v141, v141, v189, s15
	v_add3_u32 v144, v100, v190, s15
	v_add3_u32 v145, v101, v191, s15
	v_add3_u32 v102, v102, v192, s15
	v_add3_u32 v103, v103, v193, s15
	v_add3_u32 v104, v104, v194, s15
	v_add3_u32 v146, v105, v195, s15
	v_add3_u32 v105, v106, v196, s15
	v_add3_u32 v106, v107, v197, s15
	v_add3_u32 v108, v108, v198, s15
	v_add3_u32 v109, v109, v199, s15
	v_add3_u32 v107, v110, v200, s15
	v_add3_u32 v110, v111, v201, s15
	v_add3_u32 v111, v112, v202, s15
	v_add3_u32 v112, v113, v203, s15
	v_add3_u32 v113, v92, v204, s15
	v_add3_u32 v147, v93, v205, s15
	v_perm_b32 v67, v73, v72, s16
	v_perm_b32 v66, v71, v70, s16
	v_perm_b32 v69, v69, v68, s16
	v_perm_b32 v68, v143, v142, s16
	v_perm_b32 v71, v81, v80, s16
	v_perm_b32 v70, v79, v78, s16
	v_perm_b32 v73, v77, v76, s16
	v_perm_b32 v72, v75, v74, s16
	v_perm_b32 v75, v121, v120, s16
	v_perm_b32 v74, v115, v114, s16
	v_perm_b32 v77, v119, v118, s16
	v_perm_b32 v76, v117, v116, s16
	v_perm_b32 v79, v125, v124, s16
	v_perm_b32 v78, v123, v122, s16
	v_perm_b32 v81, v91, v90, s16
	v_perm_b32 v80, v89, v88, s16
	v_perm_b32 v89, v129, v128, s16
	v_perm_b32 v88, v127, v126, s16
	v_perm_b32 v91, v133, v132, s16
	v_perm_b32 v90, v131, v130, s16
	v_perm_b32 v93, v137, v136, s16
	v_perm_b32 v92, v135, v134, s16
	v_perm_b32 v101, v141, v140, s16
	v_perm_b32 v100, v139, v138, s16
	v_perm_b32 v103, v103, v102, s16
	v_perm_b32 v102, v145, v144, s16
	v_perm_b32 v105, v106, v105, s16
	v_perm_b32 v104, v146, v104, s16
	v_perm_b32 v107, v110, v107, s16
	v_perm_b32 v106, v109, v108, s16
	v_perm_b32 v109, v147, v113, s16
	v_perm_b32 v108, v112, v111, s16
	global_store_dwordx2 v[84:85], v[66:67], off offset:-4096
	global_store_dwordx2 v[84:85], v[68:69], off offset:-3584
	global_store_dwordx2 v[84:85], v[70:71], off offset:-3072
	global_store_dwordx2 v[84:85], v[72:73], off offset:-2560
	global_store_dwordx2 v[84:85], v[74:75], off offset:-2048
	global_store_dwordx2 v[84:85], v[76:77], off offset:-1536
	global_store_dwordx2 v[84:85], v[78:79], off offset:-1024
	global_store_dwordx2 v[84:85], v[80:81], off offset:-512
	global_store_dwordx2 v[84:85], v[88:89], off
	global_store_dwordx2 v[84:85], v[90:91], off offset:512
	global_store_dwordx2 v[84:85], v[92:93], off offset:1024
	global_store_dwordx2 v[84:85], v[100:101], off offset:1536
	global_store_dwordx2 v[84:85], v[102:103], off offset:2048
	global_store_dwordx2 v[84:85], v[104:105], off offset:2560
	global_store_dwordx2 v[84:85], v[106:107], off offset:3072
	global_store_dwordx2 v[84:85], v[108:109], off offset:3584
	v_lshl_add_u64 v[84:85], v[84:85], 0, s[8:9]
	s_andn2_b64 exec, exec, s[10:11]
	s_cbranch_execnz .LBB0_49
